# baseline (speedup 1.0000x reference)
; #define PG8_STAGE(bufoff, gbase, voff) do { _Pragma("unroll") for (int _i = 0; _i < 2; ++_i) \
;         __builtin_amdgcn_global_load_lds((const unsigned*)((const char*)(gbase) + (voff)[_i]), (PG8_LAS unsigned*)(lds + (bufoff) + ldsw + _i * 8192), 16, 0, 0); } while (0)
; #define PG8_WAIT_V(n) asm volatile("s_waitcnt vmcnt(" #n ")" ::: "memory")
; #define PG8_BAR __builtin_amdgcn_s_barrier()
; template <class Epi, class Sched, bool ALIGN_EPI = false, bool SP2 = false>
; __device__ __forceinline__ void gemm_phase(PG8_LAS unsigned char* lds, const Gemm g, const Sched& S, const Epi& E, const int tid) {
;     ...
;         PG8_WAIT_V(2); PG8_BAR;
;         PG8_STAGE(PG8_SB(1, 0), cB + kstep, voffB); PG8_STAGE(PG8_SA(1, 0), cA + kstep, voffA); PG8_STAGE(PG8_SB(1, 1), cB + hstep + kstep, voffB);
;         PG8_WAIT_V(6); PG8_BAR;
;     } else {
;         PG8_STAGE(PG8_SB(0, 0), cB, voffB); PG8_STAGE(PG8_SA(0, 0), cA, voffA); PG8_STAGE(PG8_SB(0, 1), cB + hstep, voffB); PG8_STAGE(PG8_SA(0, 1), cA + hstep, voffA);
;         if (wr == 1) PG8_BAR;
;         PG8_WAIT_V(4); PG8_BAR;
;         PG8_STAGE(PG8_SB(1, 0), cB + kstep, voffB); PG8_STAGE(PG8_SA(1, 0), cA + kstep, voffA); PG8_STAGE(PG8_SB(1, 1), cB + hstep + kstep, voffB);
;         PG8_WAIT_V(6); PG8_BAR;
;     }
;     for (;;) {
;         const bool has_next = S.next(ui + 1, nxt);
;         const char* nA = has_next ? (const char*)g.A + (size_t)nxt.pm * tstep : cA; const char* nB = has_next ? (const char*)g.Bt + (size_t)nxt.pn * tstep : cB;
.LBB0_607:
	s_add_i32 m0, s66, 0x18000
	v_lshl_add_u64 v[8:9], v[8:9], 0, s[28:29]
	s_waitcnt vmcnt(2)
	s_barrier
	global_load_lds_dwordx4 v[8:9], off
	v_lshl_add_u64 v[4:5], v[4:5], 0, s[28:29]
	s_add_i32 m0, s66, 0x1a000
	s_add_i32 s70, s66, 0x8000
	global_load_lds_dwordx4 v[4:5], off
	v_lshl_add_u64 v[4:5], v[6:7], 0, s[28:29]
	s_mov_b32 m0, s70
	s_add_i32 s71, s66, 0xa000
	global_load_lds_dwordx4 v[4:5], off
	v_lshl_add_u64 v[4:5], v[10:11], 0, s[28:29]
	s_mov_b32 m0, s71
	v_lshl_add_u64 v[2:3], v[2:3], 0, s[28:29]
	global_load_lds_dwordx4 v[4:5], off
	s_add_i32 m0, s66, 0x1c000
	v_lshl_add_u64 v[0:1], v[0:1], 0, s[28:29]
	global_load_lds_dwordx4 v[2:3], off
	s_add_i32 m0, s66, 0x1e000
	s_lshl_b32 s81, s26, 6
	global_load_lds_dwordx4 v[0:1], off
	v_lshlrev_b32_e32 v1, 2, v166
	v_lshl_or_b32 v0, v166, 6, v168
	s_lshl_b32 s26, s26, 13
	v_and_b32_e32 v1, 32, v1
	s_lshr_b32 s80, s6, 6
	v_bitop3_b32 v0, v0, s26, v1 bitop3:0xde
	s_lshl_b32 s26, s27, 5
	s_and_b32 s34, s26, 0x60
	s_add_i32 s82, s80, -2
	s_cmpk_lt_u32 s21, 0x100
	s_cselect_b64 s[26:27], -1, 0
	s_lshl_b32 s84, s30, 3
	v_cvt_f32_u32_e32 v1, s84
	s_lshr_b32 s85, s20, 3
	s_ashr_i32 s83, s62, 31
	s_and_b32 s86, s20, 4
	v_rcp_iflag_f32_e32 v1, v1
	s_add_i32 s87, s85, 1
	s_cmp_lg_u64 s[4:5], 0
	v_lshl_or_b32 v174, s34, 7, v169
	v_mul_f32_e32 v1, 0x4f7ffffe, v1
	v_cvt_u32_f32_e32 v1, v1
	s_cselect_b64 s[30:31], -1, 0
	v_or_b32_e32 v138, s34, v167
	s_sub_i32 s34, 0, s84
	v_readfirstlane_b32 s35, v1
	s_waitcnt vmcnt(6)
	s_mul_i32 s34, s34, s35
	s_mul_hi_u32 s34, s35, s34
	s_mov_b32 s21, s95
	s_mov_b32 s92, 0
	s_mov_b32 s98, 0
	s_add_i32 s93, s35, s34
	v_mov_b32_e32 v139, v161
	v_lshl_add_u64 v[140:141], s[94:95], 0, v[132:133]
	v_lshl_add_u64 v[142:143], s[94:95], 0, v[134:135]
	v_add_u32_e32 v175, 0, v0
	s_barrier
	s_branch .LBB0_610

; #define PG8_STAGE(bufoff, gbase, voff) do { _Pragma("unroll") for (int _i = 0; _i < 2; ++_i) \
;         __builtin_amdgcn_global_load_lds((const unsigned*)((const char*)(gbase) + (voff)[_i]), (PG8_LAS unsigned*)(lds + (bufoff) + ldsw + _i * 8192), 16, 0, 0); } while (0)
; #define PG8_LDA(dst, b, h) do { _Pragma("unroll") for (int m = 0; m < 4; ++m) _Pragma("unroll") for (int k = 0; k < 2; ++k) dst[m][k] = *(const PG8_LAS bf16x8*)(lds + PG8_SA(b, h) + aoff + m * 2048 + k * 1024); } while (0)
; #define PG8_LDB(dst, b, h) do { _Pragma("unroll") for (int n = 0; n < 2; ++n) _Pragma("unroll") for (int k = 0; k < 2; ++k) dst[n][k] = *(const PG8_LAS bf16x8*)(lds + PG8_SB(b, h) + boff + n * 2048 + k * 1024); } while (0)
; #define PG8_MMA(ai, bj, At, Bt) do { __builtin_amdgcn_s_setprio(1); _Pragma("unroll") for (int m = 0; m < 4; ++m) _Pragma("unroll") for (int n = 0; n < 2; ++n) _Pragma("unroll") for (int k = 0; k < 2; ++k) \
;         acc[ai][bj][m][n] = __builtin_amdgcn_mfma_f32_16x16x32_bf16(Bt[n][k], At[m][k], acc[ai][bj][m][n], 0, 0, 0); __builtin_amdgcn_s_setprio(0); } while (0)
; #define PG8_WAIT_V(n) asm volatile("s_waitcnt vmcnt(" #n ")" ::: "memory")
; #define PG8_WAIT_L(n) asm volatile("s_waitcnt lgkmcnt(" #n ")" ::: "memory")
; template <class Epi, class Sched, bool ALIGN_EPI = false, bool SP2 = false>
; __device__ __forceinline__ void gemm_phase(PG8_LAS unsigned char* lds, const Gemm g, const Sched& S, const Epi& E, const int tid) {
;     ...
;         const bool has_next = S.next(ui + 1, nxt);
;         const char* nA = has_next ? (const char*)g.A + (size_t)nxt.pm * tstep : cA; const char* nB = has_next ? (const char*)g.Bt + (size_t)nxt.pn * tstep : cB;
;         for (int t = 0; t < nt; t += 2) {
;             const bool last = (t == nt - 2);
;             const char* a1 = cA + (size_t)(t + 1) * kstep;
;             const char* a2 = last ? nA : cA + (size_t)(t + 2) * kstep; const char* b2 = last ? nB : cB + (size_t)(t + 2) * kstep;
;             const char* a3 = a2 + kstep; const char* b3 = b2 + kstep;
;             if (last && has_next) S.a_ready(nxt);
;             if constexpr (SP2) {
;             PG8_LDB(B0, 0, 0); PG8_LDB(B1, 0, 1); PG8_SCHED; PG8_LDA(At, 0, 0); PG8_STAGE(PG8_SA(1, 1), a1 + hstep, voffA);
;             PG8_WAIT_V(8); PG8_WAIT_L(0); PG8_BAR; PG8_MMA(0, 0, At, B0); PG8_MMA(0, 1, At, B1); PG8_BAR; PG8_SCHED;
.LBB0_620:
	s_add_u32 s44, s50, 0x80
	s_addc_u32 s45, s51, 0
	s_add_u32 s37, s48, 0x100
	s_addc_u32 s50, s49, 0
	s_mov_b32 s48, 0
	s_add_i32 s51, s48, 2
	s_add_u32 vcc_lo, s44, 0x80
	s_addc_u32 s49, s45, 0
	s_cmp_eq_u32 s82, s48
	s_cselect_b32 s49, s35, s49
	s_cselect_b32 s48, s34, vcc_lo
	v_add_u32_e32 v156, s59, v174
	s_cselect_b32 vcc_hi, s47, s50
	s_cselect_b32 vcc_lo, s46, s37
	s_add_i32 s90, 0, 0x14000
	s_waitcnt lgkmcnt(0)
	ds_read_b128 v[144:147], v156
	ds_read_b128 v[148:151], v156 offset:1024
	ds_read_b128 v[152:155], v156 offset:2048
	ds_read_b128 v[184:187], v156 offset:3072
	v_add_u32_e32 v156, s90, v174
	ds_read_b128 v[188:191], v156
	ds_read_b128 v[192:195], v156 offset:1024
	ds_read_b128 v[214:217], v156 offset:2048
	ds_read_b128 v[218:221], v156 offset:3072
	v_lshl_add_u64 v[156:157], s[44:45], 0, v[140:141]
	s_add_i32 m0, s66, 0xc000
	ds_read_b128 v[222:225], v175
	ds_read_b128 v[226:229], v175 offset:1024
	ds_read_b128 v[230:233], v175 offset:2048
	ds_read_b128 v[234:237], v175 offset:3072
	ds_read_b128 v[238:241], v175 offset:4096
	ds_read_b128 v[242:245], v175 offset:5120
	ds_read_b128 v[246:249], v175 offset:6144
	ds_read_b128 v[208:211], v175 offset:7168
	global_load_lds_dwordx4 v[156:157], off
	v_lshl_add_u64 v[156:157], s[44:45], 0, v[142:143]
	s_add_i32 m0, s66, 0xe000
	s_nop 0
	global_load_lds_dwordx4 v[156:157], off
	s_cmp_lt_u32 s98, 8
	s_cbranch_scc1 .Lmy_x8_0
	s_cmp_lt_u32 s98, 16
	s_cbranch_scc1 .Lmy_x16_0
	s_waitcnt vmcnt(24)
	s_branch .Lmy_xj_0
.Lmy_x16_0:
	s_waitcnt vmcnt(16)
	s_branch .Lmy_xj_0

; #define PG8_STAGE(bufoff, gbase, voff) do { _Pragma("unroll") for (int _i = 0; _i < 2; ++_i) \
;         __builtin_amdgcn_global_load_lds((const unsigned*)((const char*)(gbase) + (voff)[_i]), (PG8_LAS unsigned*)(lds + (bufoff) + ldsw + _i * 8192), 16, 0, 0); } while (0)
; #define PG8_LDA(dst, b, h) do { _Pragma("unroll") for (int m = 0; m < 4; ++m) _Pragma("unroll") for (int k = 0; k < 2; ++k) dst[m][k] = *(const PG8_LAS bf16x8*)(lds + PG8_SA(b, h) + aoff + m * 2048 + k * 1024); } while (0)
; #define PG8_MMA(ai, bj, At, Bt) do { __builtin_amdgcn_s_setprio(1); _Pragma("unroll") for (int m = 0; m < 4; ++m) _Pragma("unroll") for (int n = 0; n < 2; ++n) _Pragma("unroll") for (int k = 0; k < 2; ++k) \
;         acc[ai][bj][m][n] = __builtin_amdgcn_mfma_f32_16x16x32_bf16(Bt[n][k], At[m][k], acc[ai][bj][m][n], 0, 0, 0); __builtin_amdgcn_s_setprio(0); } while (0)
; #define PG8_WAIT_V(n) asm volatile("s_waitcnt vmcnt(" #n ")" ::: "memory")
; #define PG8_WAIT_L(n) asm volatile("s_waitcnt lgkmcnt(" #n ")" ::: "memory")
; #define PG8_BAR __builtin_amdgcn_s_barrier()
; #define PG8_SCHED __builtin_amdgcn_sched_barrier(0)
; template <class Epi, class Sched, bool ALIGN_EPI = false, bool SP2 = false>
; __device__ __forceinline__ void gemm_phase(PG8_LAS unsigned char* lds, const Gemm g, const Sched& S, const Epi& E, const int tid) {
;     ...
;             PG8_WAIT_V(8); PG8_WAIT_L(0); PG8_BAR; PG8_MMA(0, 0, At, B0); PG8_MMA(0, 1, At, B1); PG8_BAR; PG8_SCHED;
;             PG8_LDA(At, 0, 1); PG8_STAGE(PG8_SB(0, 0), b2, voffB); PG8_STAGE(PG8_SB(0, 1), b2 + hstep, voffB); PG8_STAGE(PG8_SA(0, 0), a2, voffA);
;             PG8_WAIT_V(8); PG8_WAIT_L(0); PG8_BAR; PG8_MMA(1, 0, At, B0); PG8_MMA(1, 1, At, B1); PG8_BAR; PG8_SCHED;
.Lmy_xj_0:
	s_waitcnt lgkmcnt(0)
	s_barrier
	s_setprio 1
	s_waitcnt lgkmcnt(0)
	v_mfma_f32_16x16x32_bf16 v[124:127], v[144:147], v[222:225], 0
	v_mfma_f32_16x16x32_bf16 v[120:123], v[152:155], v[222:225], 0
	v_mfma_f32_16x16x32_bf16 v[108:111], v[144:147], v[230:233], 0
	v_mfma_f32_16x16x32_bf16 v[104:107], v[152:155], v[230:233], 0
	v_mfma_f32_16x16x32_bf16 v[92:95], v[144:147], v[238:241], 0
	v_mfma_f32_16x16x32_bf16 v[88:91], v[152:155], v[238:241], 0
	v_mfma_f32_16x16x32_bf16 v[76:79], v[144:147], v[246:249], 0
	v_mfma_f32_16x16x32_bf16 v[72:75], v[152:155], v[246:249], 0
	v_mfma_f32_16x16x32_bf16 v[124:127], v[148:151], v[226:229], v[124:127]
	v_mfma_f32_16x16x32_bf16 v[120:123], v[184:187], v[226:229], v[120:123]
	v_mfma_f32_16x16x32_bf16 v[108:111], v[148:151], v[234:237], v[108:111]
	v_mfma_f32_16x16x32_bf16 v[104:107], v[184:187], v[234:237], v[104:107]
	v_mfma_f32_16x16x32_bf16 v[92:95], v[148:151], v[242:245], v[92:95]
	v_mfma_f32_16x16x32_bf16 v[88:91], v[184:187], v[242:245], v[88:91]
	v_mfma_f32_16x16x32_bf16 v[76:79], v[148:151], v[208:211], v[76:79]
	v_mfma_f32_16x16x32_bf16 v[72:75], v[184:187], v[208:211], v[72:75]
	s_setprio 0
	s_setprio 1
	v_mfma_f32_16x16x32_bf16 v[116:119], v[188:191], v[222:225], 0
	v_mfma_f32_16x16x32_bf16 v[112:115], v[214:217], v[222:225], 0
	v_mfma_f32_16x16x32_bf16 v[100:103], v[188:191], v[230:233], 0
	v_mfma_f32_16x16x32_bf16 v[96:99], v[214:217], v[230:233], 0
	v_mfma_f32_16x16x32_bf16 v[84:87], v[188:191], v[238:241], 0
	v_mfma_f32_16x16x32_bf16 v[80:83], v[214:217], v[238:241], 0
	v_mfma_f32_16x16x32_bf16 v[68:71], v[188:191], v[246:249], 0
	v_mfma_f32_16x16x32_bf16 v[64:67], v[214:217], v[246:249], 0
	v_mfma_f32_16x16x32_bf16 v[116:119], v[192:195], v[226:229], v[116:119]
	v_mfma_f32_16x16x32_bf16 v[112:115], v[218:221], v[226:229], v[112:115]
	v_mfma_f32_16x16x32_bf16 v[100:103], v[192:195], v[234:237], v[100:103]
	v_mfma_f32_16x16x32_bf16 v[96:99], v[218:221], v[234:237], v[96:99]
	v_mfma_f32_16x16x32_bf16 v[84:87], v[192:195], v[242:245], v[84:87]
	v_mfma_f32_16x16x32_bf16 v[80:83], v[218:221], v[242:245], v[80:83]
	v_mfma_f32_16x16x32_bf16 v[68:71], v[192:195], v[208:211], v[68:71]
	v_mfma_f32_16x16x32_bf16 v[64:67], v[218:221], v[208:211], v[64:67]
	s_setprio 0
	s_barrier
	s_add_i32 s91, s59, s65
	v_lshl_add_u64 v[156:157], vcc, 0, v[160:161]
	s_mov_b32 m0, s91
	ds_read_b128 v[208:211], v175 offset:16384
	ds_read_b128 v[222:225], v175 offset:17408
	ds_read_b128 v[226:229], v175 offset:18432
	ds_read_b128 v[230:233], v175 offset:19456
	ds_read_b128 v[234:237], v175 offset:20480
	ds_read_b128 v[238:241], v175 offset:21504
	ds_read_b128 v[242:245], v175 offset:22528
	ds_read_b128 v[246:249], v175 offset:23552
	global_load_lds_dwordx4 v[156:157], off
	s_add_i32 m0, s91, 0x2000
	v_lshl_add_u64 v[250:251], vcc, 0, v[136:137]
	s_add_u32 vcc_lo, vcc_lo, s94
	s_addc_u32 vcc_hi, vcc_hi, 0
	s_add_i32 s90, s90, s65
	global_load_lds_dwordx4 v[250:251], off
	v_lshl_add_u64 v[178:179], vcc, 0, v[160:161]
	s_mov_b32 m0, s90
	v_lshl_add_u64 v[180:181], vcc, 0, v[136:137]
	global_load_lds_dwordx4 v[178:179], off
	s_add_i32 m0, s90, 0x2000
	v_lshl_add_u64 v[204:205], s[48:49], 0, v[132:133]
	global_load_lds_dwordx4 v[180:181], off
	s_mov_b32 m0, s66
	v_lshl_add_u64 v[196:197], s[48:49], 0, v[134:135]
	global_load_lds_dwordx4 v[204:205], off
	s_mov_b32 m0, s67
	s_nop 0
	global_load_lds_dwordx4 v[196:197], off
	s_cmp_lt_u32 s98, 8
	s_cbranch_scc1 .Lmy_x8_1
	s_cmp_lt_u32 s98, 16
	s_cbranch_scc1 .Lmy_x16_1
	s_waitcnt vmcnt(24)
	s_branch .Lmy_xj_1

; #define PG8_STAGE(bufoff, gbase, voff) do { _Pragma("unroll") for (int _i = 0; _i < 2; ++_i) \
;         __builtin_amdgcn_global_load_lds((const unsigned*)((const char*)(gbase) + (voff)[_i]), (PG8_LAS unsigned*)(lds + (bufoff) + ldsw + _i * 8192), 16, 0, 0); } while (0)
; #define PG8_LDA(dst, b, h) do { _Pragma("unroll") for (int m = 0; m < 4; ++m) _Pragma("unroll") for (int k = 0; k < 2; ++k) dst[m][k] = *(const PG8_LAS bf16x8*)(lds + PG8_SA(b, h) + aoff + m * 2048 + k * 1024); } while (0)
; #define PG8_LDB(dst, b, h) do { _Pragma("unroll") for (int n = 0; n < 2; ++n) _Pragma("unroll") for (int k = 0; k < 2; ++k) dst[n][k] = *(const PG8_LAS bf16x8*)(lds + PG8_SB(b, h) + boff + n * 2048 + k * 1024); } while (0)
; #define PG8_MMA(ai, bj, At, Bt) do { __builtin_amdgcn_s_setprio(1); _Pragma("unroll") for (int m = 0; m < 4; ++m) _Pragma("unroll") for (int n = 0; n < 2; ++n) _Pragma("unroll") for (int k = 0; k < 2; ++k) \
;         acc[ai][bj][m][n] = __builtin_amdgcn_mfma_f32_16x16x32_bf16(Bt[n][k], At[m][k], acc[ai][bj][m][n], 0, 0, 0); __builtin_amdgcn_s_setprio(0); } while (0)
; #define PG8_WAIT_V(n) asm volatile("s_waitcnt vmcnt(" #n ")" ::: "memory")
; #define PG8_WAIT_L(n) asm volatile("s_waitcnt lgkmcnt(" #n ")" ::: "memory")
; #define PG8_BAR __builtin_amdgcn_s_barrier()
; #define PG8_SCHED __builtin_amdgcn_sched_barrier(0)
; template <class Epi, class Sched, bool ALIGN_EPI = false, bool SP2 = false>
; __device__ __forceinline__ void gemm_phase(PG8_LAS unsigned char* lds, const Gemm g, const Sched& S, const Epi& E, const int tid) {
;     ...
;             PG8_WAIT_V(8); PG8_WAIT_L(0); PG8_BAR; PG8_MMA(1, 0, At, B0); PG8_MMA(1, 1, At, B1); PG8_BAR; PG8_SCHED;
;             PG8_LDB(B0, 1, 0); PG8_LDB(B1, 1, 1); PG8_SCHED; PG8_LDA(At, 1, 0); PG8_STAGE(PG8_SA(0, 1), a2 + hstep, voffA);
;             PG8_WAIT_V(8); PG8_WAIT_L(0); PG8_BAR; PG8_MMA(0, 0, At, B0); PG8_MMA(0, 1, At, B1); PG8_BAR; PG8_SCHED;
.Lmy_xj_1:
	s_waitcnt lgkmcnt(0)
	s_barrier
	s_setprio 1
	s_waitcnt lgkmcnt(0)
	v_mfma_f32_16x16x32_bf16 v[60:63], v[144:147], v[208:211], 0
	v_mfma_f32_16x16x32_bf16 v[56:59], v[152:155], v[208:211], 0
	v_mfma_f32_16x16x32_bf16 v[44:47], v[144:147], v[226:229], 0
	v_mfma_f32_16x16x32_bf16 v[40:43], v[152:155], v[226:229], 0
	v_mfma_f32_16x16x32_bf16 v[28:31], v[144:147], v[234:237], 0
	v_mfma_f32_16x16x32_bf16 v[24:27], v[152:155], v[234:237], 0
	v_mfma_f32_16x16x32_bf16 v[12:15], v[144:147], v[242:245], 0
	v_mfma_f32_16x16x32_bf16 v[8:11], v[152:155], v[242:245], 0
	v_mfma_f32_16x16x32_bf16 v[60:63], v[148:151], v[222:225], v[60:63]
	v_mfma_f32_16x16x32_bf16 v[56:59], v[184:187], v[222:225], v[56:59]
	v_mfma_f32_16x16x32_bf16 v[44:47], v[148:151], v[230:233], v[44:47]
	v_mfma_f32_16x16x32_bf16 v[40:43], v[184:187], v[230:233], v[40:43]
	v_mfma_f32_16x16x32_bf16 v[28:31], v[148:151], v[238:241], v[28:31]
	v_mfma_f32_16x16x32_bf16 v[24:27], v[184:187], v[238:241], v[24:27]
	v_mfma_f32_16x16x32_bf16 v[12:15], v[148:151], v[246:249], v[12:15]
	v_mfma_f32_16x16x32_bf16 v[8:11], v[184:187], v[246:249], v[8:11]
	s_setprio 0
	s_setprio 1
	v_mfma_f32_16x16x32_bf16 v[52:55], v[188:191], v[208:211], 0
	v_mfma_f32_16x16x32_bf16 v[48:51], v[214:217], v[208:211], 0
	v_mfma_f32_16x16x32_bf16 v[36:39], v[188:191], v[226:229], 0
	v_mfma_f32_16x16x32_bf16 v[32:35], v[214:217], v[226:229], 0
	v_mfma_f32_16x16x32_bf16 v[20:23], v[188:191], v[234:237], 0
	v_mfma_f32_16x16x32_bf16 v[16:19], v[214:217], v[234:237], 0
	v_mfma_f32_16x16x32_bf16 v[4:7], v[188:191], v[242:245], 0
	v_mfma_f32_16x16x32_bf16 v[0:3], v[214:217], v[242:245], 0
	v_mfma_f32_16x16x32_bf16 v[52:55], v[192:195], v[222:225], v[52:55]
	v_mfma_f32_16x16x32_bf16 v[48:51], v[218:221], v[222:225], v[48:51]
	v_mfma_f32_16x16x32_bf16 v[36:39], v[192:195], v[230:233], v[36:39]
	v_mfma_f32_16x16x32_bf16 v[32:35], v[218:221], v[230:233], v[32:35]
	v_mfma_f32_16x16x32_bf16 v[20:23], v[192:195], v[238:241], v[20:23]
	v_mfma_f32_16x16x32_bf16 v[16:19], v[218:221], v[238:241], v[16:19]
	v_mfma_f32_16x16x32_bf16 v[4:7], v[192:195], v[246:249], v[4:7]
	v_mfma_f32_16x16x32_bf16 v[0:3], v[218:221], v[246:249], v[0:3]
	s_setprio 0
	s_barrier
	s_add_i32 s90, 0, 0x18000
	v_add_u32_e32 v183, s90, v174
	s_add_i32 s91, 0, 0x1c000
	ds_read_b128 v[144:147], v183
	ds_read_b128 v[148:151], v183 offset:1024
	ds_read_b128 v[152:155], v183 offset:2048
	ds_read_b128 v[184:187], v183 offset:3072
	v_add_u32_e32 v183, s91, v174
	ds_read_b128 v[188:191], v183
	ds_read_b128 v[192:195], v183 offset:1024
	ds_read_b128 v[208:211], v183 offset:2048
	ds_read_b128 v[214:217], v183 offset:3072
	s_add_u32 s48, s48, s94
	s_addc_u32 s49, s49, 0
	s_mov_b32 m0, s68
	v_lshl_add_u64 v[198:199], s[48:49], 0, v[132:133]
	ds_read_b128 v[218:221], v175 offset:32768
	ds_read_b128 v[222:225], v175 offset:33792
	ds_read_b128 v[226:229], v175 offset:34816
	ds_read_b128 v[230:233], v175 offset:35840
	ds_read_b128 v[234:237], v175 offset:36864
	ds_read_b128 v[238:241], v175 offset:37888
	ds_read_b128 v[242:245], v175 offset:38912
	ds_read_b128 v[246:249], v175 offset:39936
	global_load_lds_dwordx4 v[198:199], off
	v_lshl_add_u64 v[198:199], s[48:49], 0, v[134:135]
	s_mov_b32 m0, s69
	s_nop 0
	global_load_lds_dwordx4 v[198:199], off
	s_waitcnt vmcnt(8)
	s_waitcnt lgkmcnt(0)
	s_barrier
	s_setprio 1
	s_waitcnt lgkmcnt(0)
	v_mfma_f32_16x16x32_bf16 v[124:127], v[144:147], v[218:221], v[124:127]
	v_mfma_f32_16x16x32_bf16 v[120:123], v[152:155], v[218:221], v[120:123]
	v_mfma_f32_16x16x32_bf16 v[108:111], v[144:147], v[226:229], v[108:111]
	v_mfma_f32_16x16x32_bf16 v[104:107], v[152:155], v[226:229], v[104:107]
	v_mfma_f32_16x16x32_bf16 v[92:95], v[144:147], v[234:237], v[92:95]
	v_mfma_f32_16x16x32_bf16 v[88:91], v[152:155], v[234:237], v[88:91]
	v_mfma_f32_16x16x32_bf16 v[76:79], v[144:147], v[242:245], v[76:79]
	v_mfma_f32_16x16x32_bf16 v[72:75], v[152:155], v[242:245], v[72:75]
	v_mfma_f32_16x16x32_bf16 v[124:127], v[148:151], v[222:225], v[124:127]
	v_mfma_f32_16x16x32_bf16 v[120:123], v[184:187], v[222:225], v[120:123]
	v_mfma_f32_16x16x32_bf16 v[108:111], v[148:151], v[230:233], v[108:111]
	v_mfma_f32_16x16x32_bf16 v[104:107], v[184:187], v[230:233], v[104:107]
	v_mfma_f32_16x16x32_bf16 v[92:95], v[148:151], v[238:241], v[92:95]
	v_mfma_f32_16x16x32_bf16 v[88:91], v[184:187], v[238:241], v[88:91]
	v_mfma_f32_16x16x32_bf16 v[76:79], v[148:151], v[246:249], v[76:79]
	v_mfma_f32_16x16x32_bf16 v[72:75], v[184:187], v[246:249], v[72:75]
	s_setprio 0
	s_setprio 1
	v_mfma_f32_16x16x32_bf16 v[116:119], v[188:191], v[218:221], v[116:119]
	v_mfma_f32_16x16x32_bf16 v[112:115], v[208:211], v[218:221], v[112:115]
	v_mfma_f32_16x16x32_bf16 v[100:103], v[188:191], v[226:229], v[100:103]
	v_mfma_f32_16x16x32_bf16 v[96:99], v[208:211], v[226:229], v[96:99]
	v_mfma_f32_16x16x32_bf16 v[84:87], v[188:191], v[234:237], v[84:87]
	v_mfma_f32_16x16x32_bf16 v[80:83], v[208:211], v[234:237], v[80:83]
	v_mfma_f32_16x16x32_bf16 v[68:71], v[188:191], v[242:245], v[68:71]
	v_mfma_f32_16x16x32_bf16 v[64:67], v[208:211], v[242:245], v[64:67]
	v_mfma_f32_16x16x32_bf16 v[116:119], v[192:195], v[222:225], v[116:119]
	v_mfma_f32_16x16x32_bf16 v[112:115], v[214:217], v[222:225], v[112:115]
	v_mfma_f32_16x16x32_bf16 v[100:103], v[192:195], v[230:233], v[100:103]
	v_mfma_f32_16x16x32_bf16 v[96:99], v[214:217], v[230:233], v[96:99]
	v_mfma_f32_16x16x32_bf16 v[84:87], v[192:195], v[238:241], v[84:87]
	v_mfma_f32_16x16x32_bf16 v[80:83], v[214:217], v[238:241], v[80:83]
	v_mfma_f32_16x16x32_bf16 v[68:71], v[192:195], v[246:249], v[68:71]
	v_mfma_f32_16x16x32_bf16 v[64:67], v[214:217], v[246:249], v[64:67]
	s_setprio 0
	s_barrier
; #define PG8_STAGE(bufoff, gbase, voff) do { _Pragma("unroll") for (int _i = 0; _i < 2; ++_i) \
;         __builtin_amdgcn_global_load_lds((const unsigned*)((const char*)(gbase) + (voff)[_i]), (PG8_LAS unsigned*)(lds + (bufoff) + ldsw + _i * 8192), 16, 0, 0); } while (0)
; #define PG8_LDA(dst, b, h) do { _Pragma("unroll") for (int m = 0; m < 4; ++m) _Pragma("unroll") for (int k = 0; k < 2; ++k) dst[m][k] = *(const PG8_LAS bf16x8*)(lds + PG8_SA(b, h) + aoff + m * 2048 + k * 1024); } while (0)
; #define PG8_MMA(ai, bj, At, Bt) do { __builtin_amdgcn_s_setprio(1); _Pragma("unroll") for (int m = 0; m < 4; ++m) _Pragma("unroll") for (int n = 0; n < 2; ++n) _Pragma("unroll") for (int k = 0; k < 2; ++k) \
;         acc[ai][bj][m][n] = __builtin_amdgcn_mfma_f32_16x16x32_bf16(Bt[n][k], At[m][k], acc[ai][bj][m][n], 0, 0, 0); __builtin_amdgcn_s_setprio(0); } while (0)
; #define PG8_WAIT_V(n) asm volatile("s_waitcnt vmcnt(" #n ")" ::: "memory")
; #define PG8_WAIT_L(n) asm volatile("s_waitcnt lgkmcnt(" #n ")" ::: "memory")
; #define PG8_BAR __builtin_amdgcn_s_barrier()
; #define PG8_SCHED __builtin_amdgcn_sched_barrier(0)
; template <class Epi, class Sched, bool ALIGN_EPI = false, bool SP2 = false>
; __device__ __forceinline__ void gemm_phase(PG8_LAS unsigned char* lds, const Gemm g, const Sched& S, const Epi& E, const int tid) {
;     ...
;             PG8_WAIT_V(8); PG8_WAIT_L(0); PG8_BAR; PG8_MMA(0, 0, At, B0); PG8_MMA(0, 1, At, B1); PG8_BAR; PG8_SCHED;
;             PG8_LDA(At, 1, 1); PG8_STAGE(PG8_SB(1, 0), b3, voffB); PG8_STAGE(PG8_SB(1, 1), b3 + hstep, voffB); PG8_STAGE(PG8_SA(1, 0), a3, voffA);
;             PG8_WAIT_V(8); PG8_WAIT_L(0); PG8_BAR; PG8_MMA(1, 0, At, B0); PG8_MMA(1, 1, At, B1); PG8_BAR; PG8_SCHED;
	s_add_i32 s48, s90, s65
	v_lshl_add_u64 v[156:157], v[156:157], 0, s[28:29]
	s_mov_b32 m0, s48
	ds_read_b128 v[218:221], v175 offset:49152
	ds_read_b128 v[222:225], v175 offset:50176
	ds_read_b128 v[226:229], v175 offset:51200
	ds_read_b128 v[230:233], v175 offset:52224
	ds_read_b128 v[234:237], v175 offset:53248
	ds_read_b128 v[238:241], v175 offset:54272
	ds_read_b128 v[242:245], v175 offset:55296
	ds_read_b128 v[246:249], v175 offset:56320
	global_load_lds_dwordx4 v[156:157], off
	v_lshl_add_u64 v[156:157], v[250:251], 0, s[28:29]
	s_add_i32 m0, s48, 0x2000
	s_add_i32 s48, s91, s65
	global_load_lds_dwordx4 v[156:157], off
	v_lshl_add_u64 v[156:157], v[178:179], 0, s[28:29]
	s_mov_b32 m0, s48
	s_nop 0
	global_load_lds_dwordx4 v[156:157], off
	v_lshl_add_u64 v[156:157], v[180:181], 0, s[28:29]
	s_add_i32 m0, s48, 0x2000
	s_nop 0
	global_load_lds_dwordx4 v[156:157], off
	v_lshl_add_u64 v[156:157], v[204:205], 0, s[28:29]
	s_mov_b32 m0, s70
	s_nop 0
	global_load_lds_dwordx4 v[156:157], off
	v_lshl_add_u64 v[156:157], v[196:197], 0, s[28:29]
	s_mov_b32 m0, s71
	s_nop 0
	global_load_lds_dwordx4 v[156:157], off
	s_waitcnt vmcnt(8)
	s_waitcnt lgkmcnt(0)
	s_barrier
	s_setprio 1
	s_waitcnt lgkmcnt(0)
	v_mfma_f32_16x16x32_bf16 v[60:63], v[144:147], v[218:221], v[60:63]
	v_mfma_f32_16x16x32_bf16 v[56:59], v[152:155], v[218:221], v[56:59]
	v_mfma_f32_16x16x32_bf16 v[44:47], v[144:147], v[226:229], v[44:47]
	v_mfma_f32_16x16x32_bf16 v[40:43], v[152:155], v[226:229], v[40:43]
	v_mfma_f32_16x16x32_bf16 v[28:31], v[144:147], v[234:237], v[28:31]
	v_mfma_f32_16x16x32_bf16 v[24:27], v[152:155], v[234:237], v[24:27]
	v_mfma_f32_16x16x32_bf16 v[12:15], v[144:147], v[242:245], v[12:15]
	v_mfma_f32_16x16x32_bf16 v[8:11], v[152:155], v[242:245], v[8:11]
	v_mfma_f32_16x16x32_bf16 v[60:63], v[148:151], v[222:225], v[60:63]
	v_mfma_f32_16x16x32_bf16 v[56:59], v[184:187], v[222:225], v[56:59]
	v_mfma_f32_16x16x32_bf16 v[44:47], v[148:151], v[230:233], v[44:47]
	v_mfma_f32_16x16x32_bf16 v[40:43], v[184:187], v[230:233], v[40:43]
	v_mfma_f32_16x16x32_bf16 v[28:31], v[148:151], v[238:241], v[28:31]
	v_mfma_f32_16x16x32_bf16 v[24:27], v[184:187], v[238:241], v[24:27]
	v_mfma_f32_16x16x32_bf16 v[12:15], v[148:151], v[246:249], v[12:15]
	v_mfma_f32_16x16x32_bf16 v[8:11], v[184:187], v[246:249], v[8:11]
	s_setprio 0
	s_setprio 1
	v_mfma_f32_16x16x32_bf16 v[52:55], v[188:191], v[218:221], v[52:55]
	v_mfma_f32_16x16x32_bf16 v[48:51], v[208:211], v[218:221], v[48:51]
	v_mfma_f32_16x16x32_bf16 v[36:39], v[188:191], v[226:229], v[36:39]
	v_mfma_f32_16x16x32_bf16 v[32:35], v[208:211], v[226:229], v[32:35]
	v_mfma_f32_16x16x32_bf16 v[20:23], v[188:191], v[234:237], v[20:23]
	v_mfma_f32_16x16x32_bf16 v[16:19], v[208:211], v[234:237], v[16:19]
	v_mfma_f32_16x16x32_bf16 v[4:7], v[188:191], v[242:245], v[4:7]
	v_mfma_f32_16x16x32_bf16 v[0:3], v[208:211], v[242:245], v[0:3]
	v_mfma_f32_16x16x32_bf16 v[52:55], v[192:195], v[222:225], v[52:55]
	v_mfma_f32_16x16x32_bf16 v[48:51], v[214:217], v[222:225], v[48:51]
	v_mfma_f32_16x16x32_bf16 v[36:39], v[192:195], v[230:233], v[36:39]
	v_mfma_f32_16x16x32_bf16 v[32:35], v[214:217], v[230:233], v[32:35]
	v_mfma_f32_16x16x32_bf16 v[20:23], v[192:195], v[238:241], v[20:23]
	v_mfma_f32_16x16x32_bf16 v[16:19], v[214:217], v[238:241], v[16:19]
	v_mfma_f32_16x16x32_bf16 v[4:7], v[192:195], v[246:249], v[4:7]
	v_mfma_f32_16x16x32_bf16 v[0:3], v[214:217], v[246:249], v[0:3]
	s_setprio 0
	s_barrier
	s_add_u32 s44, s44, 0x100
	s_addc_u32 s45, s45, 0
	s_add_u32 s37, s37, 0x100
	s_addc_u32 s50, s50, 0
	s_cmp_ge_u32 s51, s80
	s_mov_b32 s48, s51
	s_cbranch_scc1 .Lmy_kdone_3

; DI float rowscale(const float* ss, int row) {
;     const f32x4* p = (const f32x4*)(ss + (size_t)row * 16);
;     const f32x4 a = p[0], b = p[1], c = p[2], d = p[3];
;     const float s = (((a.x + a.y) + (a.z + a.w)) + ((b.x + b.y) + (b.z + b.w))) + (((c.x + c.y) + (c.z + c.w)) + ((d.x + d.y) + (d.z + d.w)));
;     return rsqrtf(s * (1.0f / 1024.0f) + EPS);
; }
; DI void rowscales8(const float* ss, int rowbase, int fr, int fq, float (&r)[2][4]) {
;     const int lane = fq * 16 + fr;
;     const float rA = rowscale(ss, rowbase + lane), rB = rowscale(ss, rowbase + 128 + lane);
; #pragma unroll
;     for (int m = 0; m < 4; ++m) { r[0][m] = __shfl(rA, m * 16 + fr); r[1][m] = __shfl(rB, m * 16 + fr); }
; }
;     DI void operator()(const pg8::f32x4 (&acc)[2][2][4][2], const pg8::Unit& u, int wr, int wc, int fr, int fq) const {
;         const int row0 = u.pm * 256 + wr * 64 + fr, col0 = u.pn * 256 + wc * 32 + 8 * fq;
;         float rs[2][4];
;         if (ss) rowscales8(ss, u.pm * 256 + wr * 64, fr, fq, rs);
.LBB0_624:
	s_mov_b32 s98, 0
	s_lshl_b32 s37, s97, 8
	s_andn2_b64 vcc, exec, s[30:31]
	s_add_i32 s37, s37, s81
	s_cbranch_vccnz .LBB0_626
	v_or_b32_e32 v144, s37, v170
	v_ashrrev_i32_e32 v145, 31, v144
	v_lshlrev_b64 v[144:145], 6, v[144:145]
	v_lshl_add_u64 v[156:157], s[4:5], 0, v[144:145]
	global_load_dwordx4 v[144:147], v[156:157], off offset:16
	global_load_dwordx4 v[148:151], v[156:157], off offset:48
	global_load_dwordx4 v[152:155], v[156:157], off
	global_load_dwordx4 v[184:187], v[156:157], off offset:32
	v_or_b32_e32 v238, 0x80, v170
	v_add_u32_e32 v238, s37, v238
	v_ashrrev_i32_e32 v239, 31, v238
	v_lshlrev_b64 v[238:239], 6, v[238:239]
	v_lshl_add_u64 v[236:237], s[4:5], 0, v[238:239]
	global_load_dwordx4 v[220:223], v[236:237], off offset:16
	global_load_dwordx4 v[224:227], v[236:237], off offset:48
	global_load_dwordx4 v[228:231], v[236:237], off
	global_load_dwordx4 v[232:235], v[236:237], off offset:32
	s_mov_b32 s44, 0x3a800000
	s_waitcnt vmcnt(4)
	v_mov_b32_e32 v156, v152
	v_mov_b32_e32 v157, v184
	v_mov_b32_e32 v184, v153
	v_pk_add_f32 v[152:153], v[156:157], v[184:185]
	v_mov_b32_e32 v156, v154
	v_mov_b32_e32 v157, v186
	v_mov_b32_e32 v186, v155
	v_pk_add_f32 v[154:155], v[156:157], v[186:187]
	v_pk_add_f32 v[152:153], v[152:153], v[154:155]
	v_mov_b32_e32 v154, v144
	v_mov_b32_e32 v155, v148
	v_mov_b32_e32 v148, v145
	v_pk_add_f32 v[144:145], v[154:155], v[148:149]
	v_mov_b32_e32 v148, v146
	v_mov_b32_e32 v149, v150
	v_mov_b32_e32 v150, v147
	v_pk_add_f32 v[146:147], v[148:149], v[150:151]
	v_pk_add_f32 v[144:145], v[144:145], v[146:147]
	v_pk_add_f32 v[144:145], v[152:153], v[144:145]
	s_waitcnt vmcnt(0)
	v_mov_b64_e32 v[146:147], v[220:221]
	v_mov_b64_e32 v[148:149], v[222:223]
	v_mov_b64_e32 v[150:151], v[224:225]
	v_mov_b64_e32 v[152:153], v[226:227]
	v_mov_b64_e32 v[154:155], v[228:229]
	v_mov_b64_e32 v[156:157], v[230:231]
	v_mov_b64_e32 v[184:185], v[232:233]
	v_mov_b64_e32 v[186:187], v[234:235]
	v_mov_b32_e32 v178, v154
	v_mov_b32_e32 v179, v184
	v_mov_b32_e32 v184, v155
	v_pk_add_f32 v[154:155], v[178:179], v[184:185]
	v_mov_b32_e32 v178, v156
	v_mov_b32_e32 v179, v186
	v_mov_b32_e32 v186, v157
	v_pk_add_f32 v[156:157], v[178:179], v[186:187]
	v_pk_add_f32 v[154:155], v[154:155], v[156:157]
	v_mov_b32_e32 v156, v146
	v_mov_b32_e32 v157, v150
	v_mov_b32_e32 v150, v147
	v_pk_add_f32 v[146:147], v[156:157], v[150:151]
	v_mov_b32_e32 v150, v148
	v_mov_b32_e32 v151, v152
	v_mov_b32_e32 v152, v149
	v_pk_add_f32 v[148:149], v[150:151], v[152:153]
	v_pk_add_f32 v[146:147], v[146:147], v[148:149]
	v_mov_b32_e32 v149, v144
	v_pk_add_f32 v[146:147], v[154:155], v[146:147]
	v_mov_b32_e32 v148, v146
	v_mov_b32_e32 v144, v147
	v_pk_add_f32 v[144:145], v[148:149], v[144:145]
	v_pk_fma_f32 v[144:145], v[144:145], s[44:45], v[176:177] op_sel_hi:[1,0,0]
	v_mul_f32_e32 v146, 0x4b800000, v145
	v_cmp_gt_f32_e64 s[44:45], s39, v145
	v_cmp_gt_f32_e32 vcc, s39, v144
	s_nop 0
	v_cndmask_b32_e64 v145, v145, v146, s[44:45]
	v_rsq_f32_e32 v145, v145
	s_nop 0
	v_mul_f32_e32 v146, 0x45800000, v145
	v_cndmask_b32_e64 v145, v145, v146, s[44:45]
	v_mul_f32_e32 v146, 0x4b800000, v144
	v_cndmask_b32_e32 v144, v144, v146, vcc
	v_rsq_f32_e32 v144, v144
	s_nop 0
	v_mul_f32_e32 v146, 0x45800000, v144
	v_cndmask_b32_e32 v150, v144, v146, vcc
	v_and_or_b32 v144, v177, 64, v166
	v_lshlrev_b32_e32 v151, 2, v144
	ds_bpermute_b32 v152, v151, v145
	ds_bpermute_b32 v146, v151, v150
	ds_bpermute_b32 v153, v151, v145 offset:64
	ds_bpermute_b32 v147, v151, v150 offset:64
	ds_bpermute_b32 v148, v151, v145 offset:128
	ds_bpermute_b32 v144, v151, v150 offset:128
	ds_bpermute_b32 v149, v151, v145 offset:192
	ds_bpermute_b32 v145, v151, v150 offset:192
	s_branch .LBB0_627

; DI unsigned pk2(float lo, float hi) { const f32x2_t v = {lo, hi}; const bf16x2_t b = __builtin_convertvector(v, bf16x2_t); return __builtin_bit_cast(unsigned, b); }
;     DI void operator()(const pg8::f32x4 (&acc)[2][2][4][2], const pg8::Unit& u, int wr, int wc, int fr, int fq) const {
;         const int row0 = u.pm * 256 + wr * 64 + fr, col0 = u.pn * 256 + wc * 32 + 8 * fq;
;         float rs[2][4];
;         if (ss) rowscales8(ss, u.pm * 256 + wr * 64, fr, fq, rs);
;         else {
; #pragma unroll
;             for (int m = 0; m < 4; ++m) { rs[0][m] = 1.0f; rs[1][m] = 1.0f; } }
;         if (fuse_from >= 0 && u.pn >= fuse_from) {
;             const int ocol0 = 1024 + (u.pn - fuse_from) * 128 + wc * 32 + 8 * fq;
; #pragma unroll
;             for (int ai = 0; ai < 2; ++ai)
; #pragma unroll
;                 for (int m = 0; m < 4; ++m) {
;                     const int row = row0 + ai * 128 + m * 16; const float r2 = rs[ai][m] * rs[ai][m];
;                     const pg8::f32x4 g0 = acc[ai][0][m][0] * acc[ai][1][m][0] * r2, g1 = acc[ai][0][m][1] * acc[ai][1][m][1] * r2;
;                     u32x4 w; w.x = pk2(g0[0], g0[1]); w.y = pk2(g0[2], g0[3]); w.z = pk2(g1[0], g1[1]); w.w = pk2(g1[2], g1[3]);
;                     *(u32x4*)(O + (size_t)row * ldc + ocol0) = w;
;                 }
.LBB0_627:
	s_cmp_lt_i32 s96, s7
	v_or_b32_e32 v151, s37, v166
	s_cselect_b64 s[44:45], -1, 0
	s_or_b64 s[48:49], s[18:19], s[44:45]
	v_ashrrev_i32_e32 v150, 31, v151
	v_or_b32_e32 v218, 16, v151
	v_or_b32_e32 v216, 32, v151
	v_or_b32_e32 v195, 48, v151
	v_add_u32_e32 v192, 0x80, v151
	v_add_u32_e32 v189, 0x90, v151
	v_add_u32_e32 v186, 0xa0, v151
	v_add_u32_e32 v183, 0xb0, v151
	s_mov_b64 s[44:45], -1
	s_andn2_b64 vcc, exec, s[48:49]
	v_mul_lo_u32 v154, s9, v151
	v_mul_lo_u32 v214, s8, v150
	v_mul_lo_u32 v219, s9, v218
	v_mul_lo_u32 v217, s9, v216
	v_mul_lo_u32 v215, s9, v195
	v_ashrrev_i32_e32 v194, 31, v192
	v_mul_lo_u32 v193, s9, v192
	v_ashrrev_i32_e32 v191, 31, v189
	v_mul_lo_u32 v190, s9, v189
	v_ashrrev_i32_e32 v188, 31, v186
	v_mul_lo_u32 v187, s9, v186
	v_ashrrev_i32_e32 v185, 31, v183
	v_mul_lo_u32 v184, s9, v183
	s_cbranch_vccz .LBB0_630
	s_mov_b32 s98, 8
	s_waitcnt lgkmcnt(0)
	v_pk_mul_f32 v[156:157], v[152:153], v[152:153]
	v_pk_mul_f32 v[178:179], v[126:127], v[118:119]
	v_pk_mul_f32 v[180:181], v[124:125], v[116:117]
	v_pk_mul_f32 v[178:179], v[178:179], v[156:157] op_sel_hi:[1,0]
	s_sub_i32 s37, s96, s7
	v_pk_mul_f32 v[180:181], v[180:181], v[156:157] op_sel_hi:[1,0]
	v_cvt_pk_bf16_f32 v209, v178, v179
	v_mad_u64_u32 v[178:179], s[44:45], s8, v151, 0
	v_pk_mul_f32 v[196:197], v[122:123], v[114:115]
	v_pk_mul_f32 v[198:199], v[120:121], v[112:113]
	v_cvt_pk_bf16_f32 v208, v180, v181
	v_add3_u32 v179, v179, v214, v154
	v_lshl_or_b32 v180, s37, 7, v138
	v_mov_b32_e32 v181, v139
	v_pk_mul_f32 v[196:197], v[196:197], v[156:157] op_sel_hi:[1,0]
	v_pk_mul_f32 v[198:199], v[198:199], v[156:157] op_sel_hi:[1,0]
	v_lshl_add_u64 v[178:179], v[178:179], 1, s[2:3]
	v_lshlrev_b64 v[180:181], 1, v[180:181]
	v_cvt_pk_bf16_f32 v210, v198, v199
	v_cvt_pk_bf16_f32 v211, v196, v197
	v_lshl_add_u64 v[178:179], v[178:179], 0, v[180:181]
	global_store_dwordx4 v[178:179], v[208:211], off offset:2048
	v_pk_mul_f32 v[178:179], v[110:111], v[102:103]
	v_pk_mul_f32 v[196:197], v[108:109], v[100:101]
	v_pk_mul_f32 v[198:199], v[106:107], v[98:99]
	v_pk_mul_f32 v[204:205], v[104:105], v[96:97]
	v_pk_mul_f32 v[178:179], v[178:179], v[156:157] op_sel:[0,1]
	v_pk_mul_f32 v[196:197], v[196:197], v[156:157] op_sel:[0,1]
	v_pk_mul_f32 v[198:199], v[198:199], v[156:157] op_sel:[0,1]
	v_pk_mul_f32 v[156:157], v[204:205], v[156:157] op_sel:[0,1]
	v_cvt_pk_bf16_f32 v208, v196, v197
	v_cvt_pk_bf16_f32 v210, v156, v157
	v_mad_u64_u32 v[156:157], s[44:45], s8, v218, 0
	v_add3_u32 v157, v157, v214, v219
	v_lshl_add_u64 v[156:157], v[156:157], 1, s[2:3]
	v_cvt_pk_bf16_f32 v209, v178, v179
	v_cvt_pk_bf16_f32 v211, v198, v199
	v_lshl_add_u64 v[156:157], v[156:157], 0, v[180:181]
	global_store_dwordx4 v[156:157], v[208:211], off offset:2048
	v_pk_mul_f32 v[156:157], v[148:149], v[148:149]
	v_pk_mul_f32 v[178:179], v[94:95], v[86:87]
	v_pk_mul_f32 v[196:197], v[92:93], v[84:85]
	v_pk_mul_f32 v[178:179], v[178:179], v[156:157] op_sel_hi:[1,0]
	v_pk_mul_f32 v[198:199], v[90:91], v[82:83]
	v_cvt_pk_bf16_f32 v209, v178, v179
	v_mad_u64_u32 v[178:179], s[44:45], s8, v216, 0
	v_pk_mul_f32 v[204:205], v[88:89], v[80:81]
	v_add3_u32 v179, v179, v214, v217
	v_pk_mul_f32 v[196:197], v[196:197], v[156:157] op_sel_hi:[1,0]
	v_pk_mul_f32 v[198:199], v[198:199], v[156:157] op_sel_hi:[1,0]
	v_pk_mul_f32 v[204:205], v[204:205], v[156:157] op_sel_hi:[1,0]
	v_lshl_add_u64 v[178:179], v[178:179], 1, s[2:3]
	v_cvt_pk_bf16_f32 v208, v196, v197
	v_cvt_pk_bf16_f32 v210, v204, v205
	v_cvt_pk_bf16_f32 v211, v198, v199
	v_lshl_add_u64 v[178:179], v[178:179], 0, v[180:181]
	global_store_dwordx4 v[178:179], v[208:211], off offset:2048
	v_pk_mul_f32 v[178:179], v[78:79], v[70:71]
	v_pk_mul_f32 v[196:197], v[76:77], v[68:69]
	v_pk_mul_f32 v[198:199], v[74:75], v[66:67]
	v_pk_mul_f32 v[204:205], v[72:73], v[64:65]
	v_pk_mul_f32 v[178:179], v[178:179], v[156:157] op_sel:[0,1]
	v_pk_mul_f32 v[196:197], v[196:197], v[156:157] op_sel:[0,1]
	v_pk_mul_f32 v[198:199], v[198:199], v[156:157] op_sel:[0,1]
; DI unsigned pk2(float lo, float hi) { const f32x2_t v = {lo, hi}; const bf16x2_t b = __builtin_convertvector(v, bf16x2_t); return __builtin_bit_cast(unsigned, b); }
;     DI void operator()(const pg8::f32x4 (&acc)[2][2][4][2], const pg8::Unit& u, int wr, int wc, int fr, int fq) const {
;     ...
;             for (int ai = 0; ai < 2; ++ai)
; #pragma unroll
;                 for (int m = 0; m < 4; ++m) {
;                     const int row = row0 + ai * 128 + m * 16; const float r2 = rs[ai][m] * rs[ai][m];
;                     const pg8::f32x4 g0 = acc[ai][0][m][0] * acc[ai][1][m][0] * r2, g1 = acc[ai][0][m][1] * acc[ai][1][m][1] * r2;
;                     u32x4 w; w.x = pk2(g0[0], g0[1]); w.y = pk2(g0[2], g0[3]); w.z = pk2(g1[0], g1[1]); w.w = pk2(g1[2], g1[3]);
;                     *(u32x4*)(O + (size_t)row * ldc + ocol0) = w;
;                 }
	v_pk_mul_f32 v[156:157], v[204:205], v[156:157] op_sel:[0,1]
	v_cvt_pk_bf16_f32 v208, v196, v197
	v_cvt_pk_bf16_f32 v210, v156, v157
	v_mad_u64_u32 v[156:157], s[44:45], s8, v195, 0
	v_add3_u32 v157, v157, v214, v215
	v_lshl_add_u64 v[156:157], v[156:157], 1, s[2:3]
	v_cvt_pk_bf16_f32 v209, v178, v179
	v_cvt_pk_bf16_f32 v211, v198, v199
	v_lshl_add_u64 v[156:157], v[156:157], 0, v[180:181]
	global_store_dwordx4 v[156:157], v[208:211], off offset:2048
	v_pk_mul_f32 v[156:157], v[146:147], v[146:147]
	v_pk_mul_f32 v[178:179], v[62:63], v[54:55]
	v_mul_lo_u32 v150, s8, v194
	v_pk_mul_f32 v[178:179], v[178:179], v[156:157] op_sel_hi:[1,0]
	v_pk_mul_f32 v[196:197], v[60:61], v[52:53]
	v_cvt_pk_bf16_f32 v209, v178, v179
	v_mad_u64_u32 v[178:179], s[44:45], s8, v192, 0
	v_pk_mul_f32 v[198:199], v[58:59], v[50:51]
	v_pk_mul_f32 v[204:205], v[56:57], v[48:49]
	v_add3_u32 v179, v179, v150, v193
	v_pk_mul_f32 v[196:197], v[196:197], v[156:157] op_sel_hi:[1,0]
	v_pk_mul_f32 v[198:199], v[198:199], v[156:157] op_sel_hi:[1,0]
	v_pk_mul_f32 v[204:205], v[204:205], v[156:157] op_sel_hi:[1,0]
	v_lshl_add_u64 v[178:179], v[178:179], 1, s[2:3]
	v_cvt_pk_bf16_f32 v208, v196, v197
	v_cvt_pk_bf16_f32 v210, v204, v205
	v_cvt_pk_bf16_f32 v211, v198, v199
	v_lshl_add_u64 v[178:179], v[178:179], 0, v[180:181]
	global_store_dwordx4 v[178:179], v[208:211], off offset:2048
	v_pk_mul_f32 v[178:179], v[46:47], v[38:39]
	v_pk_mul_f32 v[196:197], v[44:45], v[36:37]
	v_pk_mul_f32 v[198:199], v[42:43], v[34:35]
	v_pk_mul_f32 v[204:205], v[40:41], v[32:33]
	v_pk_mul_f32 v[178:179], v[178:179], v[156:157] op_sel:[0,1]
	v_pk_mul_f32 v[196:197], v[196:197], v[156:157] op_sel:[0,1]
	v_pk_mul_f32 v[198:199], v[198:199], v[156:157] op_sel:[0,1]
	v_pk_mul_f32 v[156:157], v[204:205], v[156:157] op_sel:[0,1]
	v_mul_lo_u32 v150, s8, v191
	v_cvt_pk_bf16_f32 v210, v156, v157
	v_mad_u64_u32 v[156:157], s[44:45], s8, v189, 0
	v_add3_u32 v157, v157, v150, v190
	v_lshl_add_u64 v[156:157], v[156:157], 1, s[2:3]
	v_cvt_pk_bf16_f32 v208, v196, v197
	v_cvt_pk_bf16_f32 v209, v178, v179
	v_cvt_pk_bf16_f32 v211, v198, v199
	v_lshl_add_u64 v[156:157], v[156:157], 0, v[180:181]
	global_store_dwordx4 v[156:157], v[208:211], off offset:2048
	v_pk_mul_f32 v[156:157], v[144:145], v[144:145]
	v_pk_mul_f32 v[178:179], v[30:31], v[22:23]
	v_mul_lo_u32 v150, s8, v188
	v_pk_mul_f32 v[178:179], v[178:179], v[156:157] op_sel_hi:[1,0]
	v_pk_mul_f32 v[196:197], v[28:29], v[20:21]
	v_cvt_pk_bf16_f32 v209, v178, v179
	v_mad_u64_u32 v[178:179], s[44:45], s8, v186, 0
	v_pk_mul_f32 v[198:199], v[26:27], v[18:19]
	v_pk_mul_f32 v[204:205], v[24:25], v[16:17]
	v_add3_u32 v179, v179, v150, v187
	v_pk_mul_f32 v[196:197], v[196:197], v[156:157] op_sel_hi:[1,0]
	v_pk_mul_f32 v[198:199], v[198:199], v[156:157] op_sel_hi:[1,0]
	v_pk_mul_f32 v[204:205], v[204:205], v[156:157] op_sel_hi:[1,0]
	v_lshl_add_u64 v[178:179], v[178:179], 1, s[2:3]
	v_cvt_pk_bf16_f32 v208, v196, v197
	v_cvt_pk_bf16_f32 v210, v204, v205
	v_cvt_pk_bf16_f32 v211, v198, v199
	v_lshl_add_u64 v[178:179], v[178:179], 0, v[180:181]
	global_store_dwordx4 v[178:179], v[208:211], off offset:2048
	v_pk_mul_f32 v[178:179], v[14:15], v[6:7]
	v_pk_mul_f32 v[196:197], v[12:13], v[4:5]
	v_pk_mul_f32 v[198:199], v[10:11], v[2:3]
	v_pk_mul_f32 v[204:205], v[8:9], v[0:1]
	v_pk_mul_f32 v[178:179], v[178:179], v[156:157] op_sel:[0,1]
	v_pk_mul_f32 v[196:197], v[196:197], v[156:157] op_sel:[0,1]
	v_pk_mul_f32 v[198:199], v[198:199], v[156:157] op_sel:[0,1]
	v_pk_mul_f32 v[156:157], v[204:205], v[156:157] op_sel:[0,1]
	v_mul_lo_u32 v150, s8, v185
	v_cvt_pk_bf16_f32 v210, v156, v157
	v_mad_u64_u32 v[156:157], s[44:45], s8, v183, 0
	v_add3_u32 v157, v157, v150, v184
	v_lshl_add_u64 v[156:157], v[156:157], 1, s[2:3]
	v_cvt_pk_bf16_f32 v208, v196, v197
	v_cvt_pk_bf16_f32 v209, v178, v179
	v_cvt_pk_bf16_f32 v211, v198, v199
	v_lshl_add_u64 v[156:157], v[156:157], 0, v[180:181]
	global_store_dwordx4 v[156:157], v[208:211], off offset:2048
	s_cbranch_execz .LBB0_631

; DI unsigned pk2(float lo, float hi) { const f32x2_t v = {lo, hi}; const bf16x2_t b = __builtin_convertvector(v, bf16x2_t); return __builtin_bit_cast(unsigned, b); }
;     DI void operator()(const pg8::f32x4 (&acc)[2][2][4][2], const pg8::Unit& u, int wr, int wc, int fr, int fq) const {
;     ...
; #pragma unroll
;         for (int ai = 0; ai < 2; ++ai)
; #pragma unroll
;             for (int m = 0; m < 4; ++m) {
;                 const int row = row0 + ai * 128 + m * 16; const float r = rs[ai][m];
;                 bf16_t* rowp = O + (size_t)row * ldc;
; #pragma unroll
;                 for (int bj = 0; bj < 2; ++bj) { const int col = col0 + bj * 128;
;                     if (col < nvalid) { const pg8::f32x4 v0 = acc[ai][bj][m][0] * r, v1 = acc[ai][bj][m][1] * r;
;                         u32x4 w; w.x = pk2(v0[0], v0[1]); w.y = pk2(v0[2], v0[3]); w.z = pk2(v1[0], v1[1]); w.w = pk2(v1[2], v1[3]); *(u32x4*)(rowp + col) = w; } }
.LBB0_633:
	s_or_b64 exec, exec, s[44:45]
	s_nop 0
	v_or_b32_e32 v120, 0x80, v150
	v_cmp_gt_i32_e64 s[44:45], s60, v120
	s_cmp_lg_u64 vcc, 0
	s_cselect_b32 s98, 8, 0
	s_cmp_lg_u64 s[44:45], 0
	s_cselect_b32 s99, 8, 0
	s_add_i32 s98, s98, s99
	s_and_saveexec_b64 s[48:49], s[44:45]
	s_cbranch_execz .LBB0_635
	v_mov_b32_e32 v120, v152
	v_mov_b32_e32 v121, v152
	v_pk_mul_f32 v[118:119], v[118:119], v[120:121]
	v_pk_mul_f32 v[116:117], v[116:117], v[156:157]
	v_pk_mul_f32 v[120:121], v[114:115], v[120:121]
	v_pk_mul_f32 v[114:115], v[112:113], v[156:157]
	v_cvt_pk_bf16_f32 v112, v116, v117
	v_cvt_pk_bf16_f32 v113, v118, v119
	v_cvt_pk_bf16_f32 v114, v114, v115
	v_cvt_pk_bf16_f32 v115, v120, v121
	v_lshl_add_u64 v[116:117], v[150:151], 1, v[154:155]
	global_store_dwordx4 v[116:117], v[112:115], off offset:256
